# static s_setprio 1 for the first wave half (tid<256) in all 5 GEMM K-loops instead of the second half
# speedup vs baseline: 1.0054x; 1.0021x over previous
; template <class Epi, bool ALIGN_EPI = true, bool SP2 = true>
; __device__ __forceinline__ void gemm_phase(LAS unsigned char* lds, const Gemm g, const Order& S, const Epi& E) {
;     ...
;         const bool has_next = S.next(ui + 1, nxt);
;         const char* nA = has_next ? (const char*)(nxt.z ? g.A1 : g.A0) + (size_t)nxt.pm * tstepA + (size_t)nxt.kt0 * kstep : cA; const char* nB = has_next ? (const char*)(nxt.z ? g.B1 : g.B0) + (size_t)nxt.pn * tstepB + (size_t)nxt.kt0 * kstep : cB;
;         const int nt = cur.nkt;
;     ...
;         for (int a = 0; a < 2; ++a)
; #pragma unroll
;             for (int b = 0; b < 2; ++b)
; #pragma unroll
;                 for (int m = 0; m < 4; ++m)
; #pragma unroll
;                     for (int n = 0; n < 2; ++n) acc[a][b][m][n] = (f32x4){0.f, 0.f, 0.f, 0.f};
.LBB0_160:
	s_ashr_i32 s89, s88, 31
	s_lshl_b64 s[50:51], s[88:89], 19
	s_add_u32 s52, s23, s50
	s_addc_u32 s53, s24, s51
	s_and_b64 s[50:51], s[92:93], exec
	s_cselect_b32 s91, s53, s13
	s_cselect_b32 s90, s52, s12
	s_ashr_i32 s87, s86, 31
	s_lshl_b64 s[50:51], s[86:87], 19
	s_add_u32 s52, s60, s50
	s_addc_u32 s53, s61, s51
	s_and_b64 s[50:51], s[92:93], exec
	s_cselect_b32 s93, s53, s15
	s_cselect_b32 s92, s52, s14
	s_add_u32 s12, s12, 0x40080
	s_addc_u32 s13, s13, 0
	s_add_u32 s50, s14, 0x100
	v_mov_b32_e32 v2, 0
	s_addc_u32 s51, s15, 0
	s_mov_b32 s52, -2
	v_mov_b32_e32 v3, v2
	v_mov_b32_e32 v4, v2
	v_mov_b32_e32 v5, v2
	v_mov_b32_e32 v6, v2
	v_mov_b32_e32 v7, v2
	v_mov_b32_e32 v8, v2
	v_mov_b32_e32 v9, v2
	v_mov_b32_e32 v14, v2
	v_mov_b32_e32 v15, v2
	v_mov_b32_e32 v16, v2
	v_mov_b32_e32 v17, v2
	v_mov_b32_e32 v22, v2
	v_mov_b32_e32 v23, v2
	v_mov_b32_e32 v24, v2
	v_mov_b32_e32 v25, v2
	v_mov_b32_e32 v30, v2
	v_mov_b32_e32 v31, v2
	v_mov_b32_e32 v32, v2
	v_mov_b32_e32 v33, v2
	v_mov_b32_e32 v38, v2
	v_mov_b32_e32 v39, v2
	v_mov_b32_e32 v40, v2
	v_mov_b32_e32 v41, v2
	v_mov_b32_e32 v46, v2
	v_mov_b32_e32 v47, v2
	v_mov_b32_e32 v48, v2
	v_mov_b32_e32 v49, v2
	v_mov_b32_e32 v54, v2
	v_mov_b32_e32 v55, v2
	v_mov_b32_e32 v56, v2
	v_mov_b32_e32 v57, v2
	v_mov_b32_e32 v10, v2
	v_mov_b32_e32 v11, v2
	v_mov_b32_e32 v12, v2
	v_mov_b32_e32 v13, v2
	v_mov_b32_e32 v18, v2
	v_mov_b32_e32 v19, v2
	v_mov_b32_e32 v20, v2
	v_mov_b32_e32 v21, v2
	v_mov_b32_e32 v26, v2
	v_mov_b32_e32 v27, v2
	v_mov_b32_e32 v28, v2
	v_mov_b32_e32 v29, v2
	v_mov_b32_e32 v34, v2
	v_mov_b32_e32 v35, v2
	v_mov_b32_e32 v36, v2
	v_mov_b32_e32 v37, v2
	v_mov_b32_e32 v42, v2
	v_mov_b32_e32 v43, v2
	v_mov_b32_e32 v44, v2
	v_mov_b32_e32 v45, v2
	v_mov_b32_e32 v50, v2
	v_mov_b32_e32 v51, v2
	v_mov_b32_e32 v52, v2
	v_mov_b32_e32 v53, v2
	v_mov_b32_e32 v58, v2
	v_mov_b32_e32 v59, v2
	v_mov_b32_e32 v60, v2
	v_mov_b32_e32 v61, v2
	v_mov_b32_e32 v62, v2
	v_mov_b32_e32 v63, v2
	v_mov_b32_e32 v64, v2
	v_mov_b32_e32 v65, v2
	v_mov_b32_e32 v66, v2
	v_mov_b32_e32 v67, v2
	v_mov_b32_e32 v68, v2
	v_mov_b32_e32 v69, v2
	v_mov_b32_e32 v70, v2
	v_mov_b32_e32 v71, v2
	v_mov_b32_e32 v72, v2
	v_mov_b32_e32 v73, v2
	v_mov_b32_e32 v82, v2
	v_mov_b32_e32 v83, v2
	v_mov_b32_e32 v84, v2
	v_mov_b32_e32 v85, v2
	v_mov_b32_e32 v86, v2
	v_mov_b32_e32 v87, v2
	v_mov_b32_e32 v88, v2
	v_mov_b32_e32 v89, v2
	v_mov_b32_e32 v98, v2
	v_mov_b32_e32 v99, v2
	v_mov_b32_e32 v100, v2
	v_mov_b32_e32 v101, v2
	v_mov_b32_e32 v102, v2
	v_mov_b32_e32 v103, v2
	v_mov_b32_e32 v104, v2
	v_mov_b32_e32 v105, v2
	v_mov_b32_e32 v114, v2
	v_mov_b32_e32 v115, v2
	v_mov_b32_e32 v116, v2
	v_mov_b32_e32 v117, v2
	v_mov_b32_e32 v118, v2
	v_mov_b32_e32 v119, v2
	v_mov_b32_e32 v120, v2
	v_mov_b32_e32 v121, v2
	v_mov_b32_e32 v74, v2
	v_mov_b32_e32 v75, v2
	v_mov_b32_e32 v76, v2
	v_mov_b32_e32 v77, v2
	v_mov_b32_e32 v78, v2
	v_mov_b32_e32 v79, v2
	v_mov_b32_e32 v80, v2
	v_mov_b32_e32 v81, v2
	v_mov_b32_e32 v90, v2
	v_mov_b32_e32 v91, v2
	v_mov_b32_e32 v92, v2
	v_mov_b32_e32 v93, v2
	v_mov_b32_e32 v94, v2
	v_mov_b32_e32 v95, v2
	v_mov_b32_e32 v96, v2
	v_mov_b32_e32 v97, v2
	v_mov_b32_e32 v106, v2
	v_mov_b32_e32 v107, v2
	v_mov_b32_e32 v108, v2
	v_mov_b32_e32 v109, v2
	v_mov_b32_e32 v110, v2
	v_mov_b32_e32 v111, v2
	v_mov_b32_e32 v112, v2
	v_mov_b32_e32 v113, v2
	v_mov_b32_e32 v122, v2
	v_mov_b32_e32 v123, v2
	v_mov_b32_e32 v124, v2
	v_mov_b32_e32 v125, v2
	v_mov_b32_e32 v126, v2
	v_mov_b32_e32 v127, v2
	v_mov_b32_e32 v128, v2
	v_mov_b32_e32 v129, v2
	s_cmp_lg_u32 s80, 0
	s_cbranch_scc0 .Lsprio_skip_0
	s_setprio 1

; template <class Epi, bool ALIGN_EPI = true, bool SP2 = true>
; __device__ __forceinline__ void gemm_phase(LAS unsigned char* lds, const Gemm g, const Order& S, const Epi& E) {
;     ...
;         const int nt = cur.nkt;
;         for (int t = 0; t < nt; t += 2) {
;             const bool last = (t == nt - 2);
;             const char* a1 = cA + (size_t)(t + 1) * kstep;
;             const char* a2 = last ? nA : cA + (size_t)(t + 2) * kstep; const char* b2 = last ? nB : cB + (size_t)(t + 2) * kstep;
.LBB0_509:
	s_add_i32 s5, s19, -2
	s_add_u32 s15, s68, 0x100
	s_addc_u32 s21, s69, 0
	s_mov_b32 s24, 0
	s_cmp_lg_u32 s12, 0
	s_cbranch_scc0 .Lsprio_skip_1
	s_setprio 1

; template <class Epi, bool ALIGN_EPI = true, bool SP2 = true>
; __device__ __forceinline__ void gemm_phase(LAS unsigned char* lds, const Gemm g, const Order& S, const Epi& E) {
;     ...
;         const int nt = cur.nkt;
;         for (int t = 0; t < nt; t += 2) {
;             const bool last = (t == nt - 2);
;     ...
;         for (int a = 0; a < 2; ++a)
; #pragma unroll
;             for (int b = 0; b < 2; ++b)
; #pragma unroll
;                 for (int m = 0; m < 4; ++m)
; #pragma unroll
;                     for (int n = 0; n < 2; ++n) acc[a][b][m][n] = (f32x4){0.f, 0.f, 0.f, 0.f};
.LBB0_723:
	s_add_i32 s13, s54, -2
	s_add_u32 s15, s68, 0x100
	v_mov_b32_e32 v2, 0
	s_addc_u32 s55, s69, 0
	s_mov_b32 s57, 0
	v_mov_b32_e32 v3, v2
	v_mov_b32_e32 v4, v2
	v_mov_b32_e32 v5, v2
	v_mov_b32_e32 v6, v2
	v_mov_b32_e32 v7, v2
	v_mov_b32_e32 v8, v2
	v_mov_b32_e32 v9, v2
	v_mov_b32_e32 v18, v2
	v_mov_b32_e32 v19, v2
	v_mov_b32_e32 v20, v2
	v_mov_b32_e32 v21, v2
	v_mov_b32_e32 v22, v2
	v_mov_b32_e32 v23, v2
	v_mov_b32_e32 v24, v2
	v_mov_b32_e32 v25, v2
	v_mov_b32_e32 v34, v2
	v_mov_b32_e32 v35, v2
	v_mov_b32_e32 v36, v2
	v_mov_b32_e32 v37, v2
	v_mov_b32_e32 v38, v2
	v_mov_b32_e32 v39, v2
	v_mov_b32_e32 v40, v2
	v_mov_b32_e32 v41, v2
	v_mov_b32_e32 v50, v2
	v_mov_b32_e32 v51, v2
	v_mov_b32_e32 v52, v2
	v_mov_b32_e32 v53, v2
	v_mov_b32_e32 v54, v2
	v_mov_b32_e32 v55, v2
	v_mov_b32_e32 v56, v2
	v_mov_b32_e32 v57, v2
	v_mov_b32_e32 v10, v2
	v_mov_b32_e32 v11, v2
	v_mov_b32_e32 v12, v2
	v_mov_b32_e32 v13, v2
	v_mov_b32_e32 v14, v2
	v_mov_b32_e32 v15, v2
	v_mov_b32_e32 v16, v2
	v_mov_b32_e32 v17, v2
	v_mov_b32_e32 v26, v2
	v_mov_b32_e32 v27, v2
	v_mov_b32_e32 v28, v2
	v_mov_b32_e32 v29, v2
	v_mov_b32_e32 v30, v2
	v_mov_b32_e32 v31, v2
	v_mov_b32_e32 v32, v2
	v_mov_b32_e32 v33, v2
	v_mov_b32_e32 v42, v2
	v_mov_b32_e32 v43, v2
	v_mov_b32_e32 v44, v2
	v_mov_b32_e32 v45, v2
	v_mov_b32_e32 v46, v2
	v_mov_b32_e32 v47, v2
	v_mov_b32_e32 v48, v2
	v_mov_b32_e32 v49, v2
	v_mov_b32_e32 v58, v2
	v_mov_b32_e32 v59, v2
	v_mov_b32_e32 v60, v2
	v_mov_b32_e32 v61, v2
	v_mov_b32_e32 v62, v2
	v_mov_b32_e32 v63, v2
	v_mov_b32_e32 v64, v2
	v_mov_b32_e32 v65, v2
	v_mov_b32_e32 v66, v2
	v_mov_b32_e32 v67, v2
	v_mov_b32_e32 v68, v2
	v_mov_b32_e32 v69, v2
	v_mov_b32_e32 v70, v2
	v_mov_b32_e32 v71, v2
	v_mov_b32_e32 v72, v2
	v_mov_b32_e32 v73, v2
	v_mov_b32_e32 v82, v2
	v_mov_b32_e32 v83, v2
	v_mov_b32_e32 v84, v2
	v_mov_b32_e32 v85, v2
	v_mov_b32_e32 v86, v2
	v_mov_b32_e32 v87, v2
	v_mov_b32_e32 v88, v2
	v_mov_b32_e32 v89, v2
	v_mov_b32_e32 v98, v2
	v_mov_b32_e32 v99, v2
	v_mov_b32_e32 v100, v2
	v_mov_b32_e32 v101, v2
	v_mov_b32_e32 v102, v2
	v_mov_b32_e32 v103, v2
	v_mov_b32_e32 v104, v2
	v_mov_b32_e32 v105, v2
	v_mov_b32_e32 v114, v2
	v_mov_b32_e32 v115, v2
	v_mov_b32_e32 v116, v2
	v_mov_b32_e32 v117, v2
	v_mov_b32_e32 v118, v2
	v_mov_b32_e32 v119, v2
	v_mov_b32_e32 v120, v2
	v_mov_b32_e32 v121, v2
	v_mov_b32_e32 v74, v2
	v_mov_b32_e32 v75, v2
	v_mov_b32_e32 v76, v2
	v_mov_b32_e32 v77, v2
	v_mov_b32_e32 v78, v2
	v_mov_b32_e32 v79, v2
	v_mov_b32_e32 v80, v2
	v_mov_b32_e32 v81, v2
	v_mov_b32_e32 v90, v2
	v_mov_b32_e32 v91, v2
	v_mov_b32_e32 v92, v2
	v_mov_b32_e32 v93, v2
	v_mov_b32_e32 v94, v2
	v_mov_b32_e32 v95, v2
	v_mov_b32_e32 v96, v2
	v_mov_b32_e32 v97, v2
	v_mov_b32_e32 v106, v2
	v_mov_b32_e32 v107, v2
	v_mov_b32_e32 v108, v2
	v_mov_b32_e32 v109, v2
	v_mov_b32_e32 v110, v2
	v_mov_b32_e32 v111, v2
	v_mov_b32_e32 v112, v2
	v_mov_b32_e32 v113, v2
	v_mov_b32_e32 v122, v2
	v_mov_b32_e32 v123, v2
	v_mov_b32_e32 v124, v2
	v_mov_b32_e32 v125, v2
	v_mov_b32_e32 v126, v2
	v_mov_b32_e32 v127, v2
	v_mov_b32_e32 v128, v2
	v_mov_b32_e32 v129, v2
	s_cmp_lg_u32 s10, 0
	s_cbranch_scc0 .Lsprio_skip_2
	s_setprio 1

; template <class Epi, bool ALIGN_EPI = true, bool SP2 = true>
; __device__ __forceinline__ void gemm_phase(LAS unsigned char* lds, const Gemm g, const Order& S, const Epi& E) {
;     ...
;         const bool has_next = S.next(ui + 1, nxt);
;         const char* nA = has_next ? (const char*)(nxt.z ? g.A1 : g.A0) + (size_t)nxt.pm * tstepA + (size_t)nxt.kt0 * kstep : cA; const char* nB = has_next ? (const char*)(nxt.z ? g.B1 : g.B0) + (size_t)nxt.pn * tstepB + (size_t)nxt.kt0 * kstep : cB;
;         const int nt = cur.nkt;
;     ...
;         for (int a = 0; a < 2; ++a)
; #pragma unroll
;             for (int b = 0; b < 2; ++b)
; #pragma unroll
;                 for (int m = 0; m < 4; ++m)
; #pragma unroll
;                     for (int n = 0; n < 2; ++n) acc[a][b][m][n] = (f32x4){0.f, 0.f, 0.f, 0.f};
.LBB0_879:
	s_ashr_i32 s85, s84, 31
	s_lshl_b64 s[54:55], s[84:85], 19
	s_add_u32 s11, s50, s54
	s_addc_u32 s35, s51, s55
	s_and_b64 s[54:55], s[88:89], exec
	s_cselect_b32 s87, s35, s13
	s_cselect_b32 s86, s11, s12
	s_ashr_i32 s83, s82, 31
	s_lshl_b64 s[54:55], s[82:83], 19
	s_add_u32 s11, s52, s54
	s_addc_u32 s35, s53, s55
	s_and_b64 s[54:55], s[88:89], exec
	s_cselect_b32 s89, s35, s93
	s_cselect_b32 s88, s11, s92
	s_add_u32 s12, s12, 0x40080
	s_addc_u32 s13, s13, 0
	s_add_u32 s11, s92, 0x100
	v_mov_b32_e32 v2, 0
	s_addc_u32 s35, s93, 0
	s_mov_b32 s54, -2
	v_mov_b32_e32 v3, v2
	v_mov_b32_e32 v4, v2
	v_mov_b32_e32 v5, v2
	v_mov_b32_e32 v14, v2
	v_mov_b32_e32 v15, v2
	v_mov_b32_e32 v16, v2
	v_mov_b32_e32 v17, v2
	v_mov_b32_e32 v18, v2
	v_mov_b32_e32 v19, v2
	v_mov_b32_e32 v20, v2
	v_mov_b32_e32 v21, v2
	v_mov_b32_e32 v30, v2
	v_mov_b32_e32 v31, v2
	v_mov_b32_e32 v32, v2
	v_mov_b32_e32 v33, v2
	v_mov_b32_e32 v34, v2
	v_mov_b32_e32 v35, v2
	v_mov_b32_e32 v36, v2
	v_mov_b32_e32 v37, v2
	v_mov_b32_e32 v46, v2
	v_mov_b32_e32 v47, v2
	v_mov_b32_e32 v48, v2
	v_mov_b32_e32 v49, v2
	v_mov_b32_e32 v82, v2
	v_mov_b32_e32 v83, v2
	v_mov_b32_e32 v84, v2
	v_mov_b32_e32 v85, v2
	v_mov_b32_e32 v94, v2
	v_mov_b32_e32 v95, v2
	v_mov_b32_e32 v96, v2
	v_mov_b32_e32 v97, v2
	v_mov_b32_e32 v6, v2
	v_mov_b32_e32 v7, v2
	v_mov_b32_e32 v8, v2
	v_mov_b32_e32 v9, v2
	v_mov_b32_e32 v10, v2
	v_mov_b32_e32 v11, v2
	v_mov_b32_e32 v12, v2
	v_mov_b32_e32 v13, v2
	v_mov_b32_e32 v22, v2
	v_mov_b32_e32 v23, v2
	v_mov_b32_e32 v24, v2
	v_mov_b32_e32 v25, v2
	v_mov_b32_e32 v26, v2
	v_mov_b32_e32 v27, v2
	v_mov_b32_e32 v28, v2
	v_mov_b32_e32 v29, v2
	v_mov_b32_e32 v38, v2
	v_mov_b32_e32 v39, v2
	v_mov_b32_e32 v40, v2
	v_mov_b32_e32 v41, v2
	v_mov_b32_e32 v42, v2
	v_mov_b32_e32 v43, v2
	v_mov_b32_e32 v44, v2
	v_mov_b32_e32 v45, v2
	v_mov_b32_e32 v86, v2
	v_mov_b32_e32 v87, v2
	v_mov_b32_e32 v88, v2
	v_mov_b32_e32 v89, v2
	v_mov_b32_e32 v90, v2
	v_mov_b32_e32 v91, v2
	v_mov_b32_e32 v92, v2
	v_mov_b32_e32 v93, v2
	v_mov_b32_e32 v106, v2
	v_mov_b32_e32 v107, v2
	v_mov_b32_e32 v108, v2
	v_mov_b32_e32 v109, v2
	v_mov_b32_e32 v114, v2
	v_mov_b32_e32 v115, v2
	v_mov_b32_e32 v116, v2
	v_mov_b32_e32 v117, v2
	v_mov_b32_e32 v122, v2
	v_mov_b32_e32 v123, v2
	v_mov_b32_e32 v124, v2
	v_mov_b32_e32 v125, v2
	v_mov_b32_e32 v130, v2
	v_mov_b32_e32 v131, v2
	v_mov_b32_e32 v132, v2
	v_mov_b32_e32 v133, v2
	v_mov_b32_e32 v138, v2
	v_mov_b32_e32 v139, v2
	v_mov_b32_e32 v140, v2
	v_mov_b32_e32 v141, v2
	v_mov_b32_e32 v146, v2
	v_mov_b32_e32 v147, v2
	v_mov_b32_e32 v148, v2
	v_mov_b32_e32 v149, v2
	v_mov_b32_e32 v154, v2
	v_mov_b32_e32 v155, v2
	v_mov_b32_e32 v156, v2
	v_mov_b32_e32 v157, v2
	v_mov_b32_e32 v158, v2
	v_mov_b32_e32 v159, v2
	v_mov_b32_e32 v160, v2
	v_mov_b32_e32 v161, v2
	v_mov_b32_e32 v98, v2
	v_mov_b32_e32 v99, v2
	v_mov_b32_e32 v100, v2
	v_mov_b32_e32 v101, v2
	v_mov_b32_e32 v102, v2
	v_mov_b32_e32 v103, v2
	v_mov_b32_e32 v104, v2
	v_mov_b32_e32 v105, v2
	v_mov_b32_e32 v110, v2
	v_mov_b32_e32 v111, v2
	v_mov_b32_e32 v112, v2
	v_mov_b32_e32 v113, v2
	v_mov_b32_e32 v118, v2
	v_mov_b32_e32 v119, v2
	v_mov_b32_e32 v120, v2
	v_mov_b32_e32 v121, v2
	v_mov_b32_e32 v126, v2
	v_mov_b32_e32 v127, v2
	v_mov_b32_e32 v128, v2
	v_mov_b32_e32 v129, v2
	v_mov_b32_e32 v134, v2
	v_mov_b32_e32 v135, v2
	v_mov_b32_e32 v136, v2
	v_mov_b32_e32 v137, v2
	v_mov_b32_e32 v142, v2
	v_mov_b32_e32 v143, v2
	v_mov_b32_e32 v144, v2
	v_mov_b32_e32 v145, v2
	v_mov_b32_e32 v150, v2
	v_mov_b32_e32 v151, v2
	v_mov_b32_e32 v152, v2
	v_mov_b32_e32 v153, v2
	s_cmp_lg_u32 s76, 0
	s_cbranch_scc0 .Lsprio_skip_3
	s_setprio 1

; template <class Epi, bool ALIGN_EPI = true, bool SP2 = true>
; __device__ __forceinline__ void gemm_phase(LAS unsigned char* lds, const Gemm g, const Order& S, const Epi& E) {
;     ...
;         const int nt = cur.nkt;
;         for (int t = 0; t < nt; t += 2) {
;             const bool last = (t == nt - 2);
;             const char* a1 = cA + (size_t)(t + 1) * kstep;
;             const char* a2 = last ? nA : cA + (size_t)(t + 2) * kstep; const char* b2 = last ? nB : cB + (size_t)(t + 2) * kstep;
;             const char* a3 = a2 + kstep; const char* b3 = b2 + kstep;
;     ...
;         for (int a = 0; a < 2; ++a)
; #pragma unroll
;             for (int b = 0; b < 2; ++b)
; #pragma unroll
;                 for (int m = 0; m < 4; ++m)
; #pragma unroll
;                     for (int n = 0; n < 2; ++n) acc[a][b][m][n] = (f32x4){0.f, 0.f, 0.f, 0.f};
.LBB0_1096:
	s_add_i32 s13, s55, -2
	s_add_u32 s59, s62, 0x100
	v_mov_b32_e32 v2, 0
	s_addc_u32 s69, s63, 0
	s_mov_b32 s64, 0
	v_mov_b32_e32 v3, v2
	v_mov_b32_e32 v4, v2
	v_mov_b32_e32 v5, v2
	v_mov_b32_e32 v6, v2
	v_mov_b32_e32 v7, v2
	v_mov_b32_e32 v8, v2
	v_mov_b32_e32 v9, v2
	v_mov_b32_e32 v18, v2
	v_mov_b32_e32 v19, v2
	v_mov_b32_e32 v20, v2
	v_mov_b32_e32 v21, v2
	v_mov_b32_e32 v22, v2
	v_mov_b32_e32 v23, v2
	v_mov_b32_e32 v24, v2
	v_mov_b32_e32 v25, v2
	v_mov_b32_e32 v34, v2
	v_mov_b32_e32 v35, v2
	v_mov_b32_e32 v36, v2
	v_mov_b32_e32 v37, v2
	v_mov_b32_e32 v38, v2
	v_mov_b32_e32 v39, v2
	v_mov_b32_e32 v40, v2
	v_mov_b32_e32 v41, v2
	v_mov_b32_e32 v50, v2
	v_mov_b32_e32 v51, v2
	v_mov_b32_e32 v52, v2
	v_mov_b32_e32 v53, v2
	v_mov_b32_e32 v54, v2
	v_mov_b32_e32 v55, v2
	v_mov_b32_e32 v56, v2
	v_mov_b32_e32 v57, v2
	v_mov_b32_e32 v10, v2
	v_mov_b32_e32 v11, v2
	v_mov_b32_e32 v12, v2
	v_mov_b32_e32 v13, v2
	v_mov_b32_e32 v14, v2
	v_mov_b32_e32 v15, v2
	v_mov_b32_e32 v16, v2
	v_mov_b32_e32 v17, v2
	v_mov_b32_e32 v26, v2
	v_mov_b32_e32 v27, v2
	v_mov_b32_e32 v28, v2
	v_mov_b32_e32 v29, v2
	v_mov_b32_e32 v30, v2
	v_mov_b32_e32 v31, v2
	v_mov_b32_e32 v32, v2
	v_mov_b32_e32 v33, v2
	v_mov_b32_e32 v42, v2
	v_mov_b32_e32 v43, v2
	v_mov_b32_e32 v44, v2
	v_mov_b32_e32 v45, v2
	v_mov_b32_e32 v46, v2
	v_mov_b32_e32 v47, v2
	v_mov_b32_e32 v48, v2
	v_mov_b32_e32 v49, v2
	v_mov_b32_e32 v58, v2
	v_mov_b32_e32 v59, v2
	v_mov_b32_e32 v60, v2
	v_mov_b32_e32 v61, v2
	v_mov_b32_e32 v62, v2
	v_mov_b32_e32 v63, v2
	v_mov_b32_e32 v64, v2
	v_mov_b32_e32 v65, v2
	v_mov_b32_e32 v66, v2
	v_mov_b32_e32 v67, v2
	v_mov_b32_e32 v68, v2
	v_mov_b32_e32 v69, v2
	v_mov_b32_e32 v70, v2
	v_mov_b32_e32 v71, v2
	v_mov_b32_e32 v72, v2
	v_mov_b32_e32 v73, v2
	v_mov_b32_e32 v82, v2
	v_mov_b32_e32 v83, v2
	v_mov_b32_e32 v84, v2
	v_mov_b32_e32 v85, v2
	v_mov_b32_e32 v86, v2
	v_mov_b32_e32 v87, v2
	v_mov_b32_e32 v88, v2
	v_mov_b32_e32 v89, v2
	v_mov_b32_e32 v98, v2
	v_mov_b32_e32 v99, v2
	v_mov_b32_e32 v100, v2
	v_mov_b32_e32 v101, v2
	v_mov_b32_e32 v102, v2
	v_mov_b32_e32 v103, v2
	v_mov_b32_e32 v104, v2
	v_mov_b32_e32 v105, v2
	v_mov_b32_e32 v114, v2
	v_mov_b32_e32 v115, v2
	v_mov_b32_e32 v116, v2
	v_mov_b32_e32 v117, v2
	v_mov_b32_e32 v118, v2
	v_mov_b32_e32 v119, v2
	v_mov_b32_e32 v120, v2
	v_mov_b32_e32 v121, v2
	v_mov_b32_e32 v74, v2
	v_mov_b32_e32 v75, v2
	v_mov_b32_e32 v76, v2
	v_mov_b32_e32 v77, v2
	v_mov_b32_e32 v78, v2
	v_mov_b32_e32 v79, v2
	v_mov_b32_e32 v80, v2
	v_mov_b32_e32 v81, v2
	v_mov_b32_e32 v90, v2
	v_mov_b32_e32 v91, v2
	v_mov_b32_e32 v92, v2
	v_mov_b32_e32 v93, v2
	v_mov_b32_e32 v94, v2
	v_mov_b32_e32 v95, v2
	v_mov_b32_e32 v96, v2
	v_mov_b32_e32 v97, v2
	v_mov_b32_e32 v106, v2
	v_mov_b32_e32 v107, v2
	v_mov_b32_e32 v108, v2
	v_mov_b32_e32 v109, v2
	v_mov_b32_e32 v110, v2
	v_mov_b32_e32 v111, v2
	v_mov_b32_e32 v112, v2
	v_mov_b32_e32 v113, v2
	v_mov_b32_e32 v122, v2
	v_mov_b32_e32 v123, v2
	v_mov_b32_e32 v124, v2
	v_mov_b32_e32 v125, v2
	v_mov_b32_e32 v126, v2
	v_mov_b32_e32 v127, v2
	v_mov_b32_e32 v128, v2
	v_mov_b32_e32 v129, v2
	s_cmp_lg_u32 s10, 0
	s_cbranch_scc0 .Lsprio_skip_4
	s_setprio 1
